# LN1 (phase 11): ln weight/bias slices loaded once per wave, adaLN scale/shift prefetched 3 blocks ahead with counted waits
# speedup vs baseline: 1.1273x; 1.0140x over previous
.LBB0_2246:
	s_cmp_lt_i32 s4, 12
	s_cselect_b64 s[0:1], -1, 0
	s_cmp_gt_i32 s5, 11
	s_cselect_b64 s[2:3], -1, 0
	s_and_b64 s[0:1], s[0:1], s[2:3]
	s_andn2_b64 vcc, exec, s[0:1]
	v_lshrrev_b32_e32 v156, 6, v34
	s_cbranch_vccnz .LBB0_2342
	s_waitcnt vmcnt(0)
	v_lshl_add_u32 v36, s28, 3, v156
	s_movk_i32 s0, 0x2100
	v_cmp_gt_i32_e32 vcc, s0, v36
	s_and_saveexec_b64 s[6:7], vcc
	s_cbranch_execz .LBB0_2274
	v_lshlrev_b32_e32 v2, 2, v34
	v_and_b32_e32 v38, 0xfc, v2
	v_readlane_b32 s12, v254, 50
	v_mov_b32_e32 v41, 0
	v_lshlrev_b32_e32 v40, 1, v38
	v_readlane_b32 s14, v254, 52
	v_readlane_b32 s15, v254, 53
	v_readlane_b32 s16, v254, 54
	v_readlane_b32 s17, v254, 55
	v_readlane_b32 s18, v254, 56
	v_readlane_b32 s19, v254, 57
	v_readlane_b32 s20, v254, 58
	v_readlane_b32 s21, v254, 59
	s_add_u32 s8, s34, 0x8240000
	v_lshl_add_u64 v[2:3], s[34:35], 0, v[40:41]
	v_or_b32_e32 v46, 0x400, v38
	v_lshlrev_b32_e32 v40, 2, v38
	s_mov_b64 s[14:15], s[18:19]
	s_mov_b64 s[16:17], s[20:21]
	s_addc_u32 s9, s35, 0
	v_or_b32_e32 v48, 0x500, v38
	v_lshl_add_u64 v[54:55], s[14:15], 0, v[40:41]
	v_lshl_add_u64 v[56:57], s[16:17], 0, v[40:41]
	v_lshlrev_b32_e32 v40, 2, v46
	s_add_u32 s10, s34, 0xb222200
	v_or_b32_e32 v50, 0x600, v38
	v_lshl_add_u64 v[58:59], s[14:15], 0, v[40:41]
	v_lshl_add_u64 v[60:61], s[16:17], 0, v[40:41]
	v_lshlrev_b32_e32 v40, 2, v48
	s_addc_u32 s11, s35, 0
	s_mov_b64 s[0:1], 0x9122200
	v_or_b32_e32 v52, 0x700, v38
	v_lshl_add_u64 v[62:63], s[14:15], 0, v[40:41]
	v_lshl_add_u64 v[64:65], s[16:17], 0, v[40:41]
	v_lshlrev_b32_e32 v40, 2, v50
	v_lshl_add_u64 v[42:43], v[2:3], 0, s[0:1]
	v_or_b32_e32 v2, 0x100, v38
	v_or_b32_e32 v4, 0x200, v38
	v_readlane_b32 s13, v254, 51
	v_readlane_b32 s22, v254, 60
	v_readlane_b32 s23, v254, 61
	v_readlane_b32 s24, v254, 62
	v_readlane_b32 s25, v254, 63
	v_lshl_add_u64 v[66:67], s[14:15], 0, v[40:41]
	v_lshl_add_u64 v[68:69], s[16:17], 0, v[40:41]
	v_lshlrev_b32_e32 v40, 2, v52
	s_add_u32 s12, s34, 0x1eda2200
	v_or_b32_e32 v44, 0x300, v38
	v_lshl_add_u64 v[70:71], s[14:15], 0, v[40:41]
	v_lshl_add_u64 v[72:73], s[16:17], 0, v[40:41]
	s_addc_u32 s13, s35, 0
	s_lshl_b32 s3, s88, 3
	s_mov_b64 s[14:15], 0
	s_movk_i32 s4, 0x2080
	s_movk_i32 s5, 0x1fff
	s_movk_i32 s19, 0x2000
	s_mov_b32 s30, 0xc000
	s_mov_b64 s[16:17], 0x4000
	s_mov_b32 s18, 0x3f9837f0
	s_mov_b32 s20, 0
	v_mov_b32_e32 v35, 0x3727c5ac
	s_mov_b32 s33, 0x800000
	s_mov_b64 s[22:23], 0x8000
	s_mov_b64 s[24:25], 0x6000
	s_movk_i32 s36, 0x20ff
	v_lshlrev_b32_e32 v40, 2, v38
	v_lshlrev_b32_e32 v74, 2, v2
	v_lshlrev_b32_e32 v76, 2, v4
	v_readlane_b32 s26, v255, 0
	v_readlane_b32 s27, v255, 1
	global_load_dwordx4 v[174:177], v[54:55], off
	global_load_dwordx4 v[182:185], v[54:55], off offset:1024
	global_load_dwordx4 v[190:193], v[54:55], off offset:2048
	global_load_dwordx4 v[198:201], v[54:55], off offset:3072
	global_load_dwordx4 v[178:181], v[56:57], off
	global_load_dwordx4 v[186:189], v[56:57], off offset:1024
	global_load_dwordx4 v[194:197], v[56:57], off offset:2048
	global_load_dwordx4 v[202:205], v[56:57], off offset:3072
	global_load_dwordx4 v[206:209], v[58:59], off
	global_load_dwordx4 v[210:213], v[60:61], off
	global_load_dwordx4 v[214:217], v[62:63], off
	global_load_dwordx4 v[218:221], v[64:65], off
	global_load_dwordx4 v[222:225], v[66:67], off
	global_load_dwordx4 v[226:229], v[68:69], off
	global_load_dwordx4 v[230:233], v[70:71], off
	global_load_dwordx4 v[234:237], v[72:73], off
	s_branch .LBB0_2250

.LBB0_2255:
	s_or_b64 exec, exec, s[0:1]
	v_readfirstlane_b32 s98, v88
	v_readfirstlane_b32 s99, v89
	s_add_u32 s100, s98, 0x7000
	s_addc_u32 s101, s99, 0
	s_add_u32 s98, s98, 0x9000
	s_addc_u32 s99, s99, 0
	global_load_dwordx4 v[238:241], v40, s[98:99] offset:-4096
	global_load_dwordx4 v[242:245], v40, s[100:101] offset:-4096
	global_load_dwordx4 v[246:249], v40, s[98:99] offset:-3072
	global_load_dwordx4 v[250:253], v40, s[100:101] offset:-3072
	global_load_dwordx4 v[158:161], v40, s[98:99] offset:-2048
	global_load_dwordx4 v[162:165], v40, s[100:101] offset:-2048
	v_mov_b32_e32 v94, v6
	v_mov_b32_e32 v95, v2
	v_mov_b32_e32 v96, v7
	v_mov_b32_e32 v97, v3
	v_pk_add_f32 v[94:95], v[94:95], v[96:97]
	v_mov_b32_e32 v96, v8
	v_mov_b32_e32 v97, v4
	v_mov_b32_e32 v98, v9
	v_mov_b32_e32 v99, v5
	v_pk_add_f32 v[96:97], v[96:97], v[98:99]
	v_mov_b32_e32 v98, v10
	v_pk_add_f32 v[94:95], v[94:95], v[96:97]
	v_mov_b32_e32 v96, v11
	v_mov_b32_e32 v97, v12
	v_mov_b32_e32 v99, v13
	v_pk_add_f32 v[96:97], v[96:97], v[98:99]
	v_add_f32_e32 v39, 0, v95
	v_pk_add_f32 v[96:97], v[96:97], v[96:97] op_sel_hi:[0,1]
	v_add_f32_e32 v95, v94, v39
	v_add_f32_e32 v99, v14, v15
	v_add_f32_e32 v101, v16, v17
	v_mov_b32_e32 v98, v18
	v_mov_b32_e32 v100, v19
	v_mov_b32_e32 v96, v20
	v_mov_b32_e32 v94, v21
	v_pk_add_f32 v[98:99], v[98:99], v[100:101]
	v_pk_add_f32 v[94:95], v[96:97], v[94:95]
	v_mov_b32_e32 v96, v23
	v_pk_add_f32 v[94:95], v[98:99], v[94:95]
	v_mov_b32_e32 v97, v24
	v_mov_b32_e32 v98, v22
	v_mov_b32_e32 v99, v25
	v_pk_add_f32 v[96:97], v[96:97], v[98:99]
	v_pk_add_f32 v[94:95], v[94:95], v[94:95] op_sel_hi:[0,1]
	v_pk_add_f32 v[96:97], v[96:97], v[96:97] op_sel_hi:[0,1]
	v_add_f32_e32 v99, v26, v27
	v_add_f32_e32 v101, v28, v29
	v_mov_b32_e32 v98, v30
	v_mov_b32_e32 v100, v31
	v_mov_b32_e32 v96, v32
	v_mov_b32_e32 v94, v33
	v_pk_add_f32 v[98:99], v[98:99], v[100:101]
	v_pk_add_f32 v[94:95], v[96:97], v[94:95]
	v_mov_b32_e32 v93, v41
	v_pk_add_f32 v[94:95], v[98:99], v[94:95]
	s_nop 0
	v_add_f32_e32 v39, v94, v95
	s_nop 1
	v_add_f32_dpp v39, v39, v39 quad_perm:[1,0,3,2] row_mask:0xf bank_mask:0xf bound_ctrl:1
	s_nop 1
	v_add_f32_dpp v39, v39, v39 quad_perm:[2,3,0,1] row_mask:0xf bank_mask:0xf bound_ctrl:1
	s_nop 1
	v_add_f32_dpp v39, v39, v39 row_half_mirror row_mask:0xf bank_mask:0xf bound_ctrl:1
	s_nop 1
	v_add_f32_dpp v39, v39, v39 row_mirror row_mask:0xf bank_mask:0xf bound_ctrl:1
	s_nop 0
	v_readlane_b32 s2, v39, 16
	v_readlane_b32 s21, v39, 48
	v_readlane_b32 s0, v39, 0
	v_readlane_b32 s1, v39, 32
	v_mov_b32_e32 v94, s2
	v_mov_b32_e32 v95, s21
	v_pk_add_f32 v[94:95], s[0:1], v[94:95]
	s_nop 0
	v_add_f32_e32 v39, v94, v95
	v_fmamk_f32 v121, v39, 0xba000000, v5
	v_fmamk_f32 v123, v39, 0xba000000, v3
	v_fmamk_f32 v120, v39, 0xba000000, v4
	v_fmamk_f32 v122, v39, 0xba000000, v2
	v_fmamk_f32 v105, v39, 0xba000000, v9
	v_fmamk_f32 v107, v39, 0xba000000, v7
	v_mov_b32_e32 v106, v123
	v_mov_b32_e32 v104, v121
	v_fmamk_f32 v109, v39, 0xba000000, v8
	v_fmamk_f32 v111, v39, 0xba000000, v6
	v_mov_b32_e32 v110, v122
	v_pk_mul_f32 v[2:3], v[106:107], v[106:107]
	v_mov_b32_e32 v108, v120
	v_pk_mul_f32 v[4:5], v[104:105], v[104:105]
	v_pk_fma_f32 v[2:3], v[110:111], v[110:111], v[2:3]
	v_pk_fma_f32 v[4:5], v[108:109], v[108:109], v[4:5]
	v_fmamk_f32 v99, v39, 0xba000000, v13
	v_pk_add_f32 v[2:3], v[2:3], v[4:5]
	v_fmamk_f32 v98, v39, 0xba000000, v12
	v_pk_add_f32 v[6:7], v[2:3], v[2:3] op_sel_hi:[0,1]
	v_fmamk_f32 v103, v39, 0xba000000, v11
	v_fmamk_f32 v102, v39, 0xba000000, v10
	v_pk_mul_f32 v[8:9], v[98:99], v[98:99]
	v_pk_mul_f32 v[10:11], v[102:103], v[102:103]
	v_fmamk_f32 v114, v39, 0xba000000, v14
	v_pk_mov_b32 v[12:13], v[10:11], v[8:9] op_sel:[1,0]
	v_mov_b32_e32 v11, v9
	v_fmamk_f32 v112, v39, 0xba000000, v16
	v_fmamk_f32 v115, v39, 0xba000000, v15
	v_mul_f32_e32 v6, v114, v114
	v_pk_add_f32 v[8:9], v[12:13], v[10:11]
	v_fmamk_f32 v113, v39, 0xba000000, v17
	v_pk_fma_f32 v[10:11], v[114:115], v[114:115], v[6:7] op_sel_hi:[1,1,0]
	v_mul_f32_e32 v6, v112, v112
	v_pk_add_f32 v[8:9], v[8:9], v[8:9] op_sel_hi:[0,1]
	v_pk_fma_f32 v[12:13], v[112:113], v[112:113], v[6:7] op_sel_hi:[1,1,0]
	v_fmamk_f32 v97, v39, 0xba000000, v21
	v_fmamk_f32 v96, v39, 0xba000000, v20
	v_fmamk_f32 v101, v39, 0xba000000, v19
	v_fmamk_f32 v100, v39, 0xba000000, v18
	v_mul_f32_e32 v10, v100, v100
	v_mul_f32_e32 v12, v101, v101
	v_mul_f32_e32 v8, v96, v96
	v_mul_f32_e32 v6, v97, v97
	v_pk_add_f32 v[10:11], v[10:11], v[12:13]
	v_pk_add_f32 v[6:7], v[8:9], v[6:7]
	v_fmamk_f32 v25, v39, 0xba000000, v25
	v_pk_add_f32 v[6:7], v[10:11], v[6:7]
	v_fmamk_f32 v24, v39, 0xba000000, v24
	v_fmamk_f32 v95, v39, 0xba000000, v23
	v_fmamk_f32 v94, v39, 0xba000000, v22
	v_pk_add_f32 v[8:9], v[6:7], v[6:7] op_sel_hi:[0,1]
	v_pk_mul_f32 v[6:7], v[24:25], v[24:25]
	v_pk_mul_f32 v[10:11], v[94:95], v[94:95]
	v_fmamk_f32 v22, v39, 0xba000000, v26
	v_pk_mov_b32 v[12:13], v[10:11], v[6:7] op_sel:[1,0]
	v_mov_b32_e32 v11, v7
	v_pk_add_f32 v[6:7], v[12:13], v[10:11]
	v_fmamk_f32 v20, v39, 0xba000000, v28
	v_pk_add_f32 v[10:11], v[6:7], v[6:7] op_sel_hi:[0,1]
	v_fmamk_f32 v23, v39, 0xba000000, v27
	v_mul_f32_e32 v6, v22, v22
	v_fmamk_f32 v21, v39, 0xba000000, v29
	v_pk_fma_f32 v[12:13], v[22:23], v[22:23], v[6:7] op_sel_hi:[1,1,0]
	v_mul_f32_e32 v6, v20, v20
	v_pk_fma_f32 v[14:15], v[20:21], v[20:21], v[6:7] op_sel_hi:[1,1,0]
	v_fmamk_f32 v7, v39, 0xba000000, v33
	v_fmamk_f32 v6, v39, 0xba000000, v32
	v_fmamk_f32 v31, v39, 0xba000000, v31
	v_fmac_f32_e32 v30, 0xba000000, v39
	v_mul_f32_e32 v12, v30, v30
	v_mul_f32_e32 v14, v31, v31
	v_mul_f32_e32 v10, v6, v6
	v_mul_f32_e32 v8, v7, v7
	v_pk_add_f32 v[12:13], v[12:13], v[14:15]
	v_pk_add_f32 v[8:9], v[10:11], v[8:9]
	v_lshlrev_b64 v[18:19], 11, v[36:37]
	v_pk_add_f32 v[8:9], v[12:13], v[8:9]
	s_nop 0
	v_add_f32_e32 v8, v8, v9
	s_nop 1
	v_add_f32_dpp v8, v8, v8 quad_perm:[1,0,3,2] row_mask:0xf bank_mask:0xf bound_ctrl:1
	s_nop 1
	v_add_f32_dpp v8, v8, v8 quad_perm:[2,3,0,1] row_mask:0xf bank_mask:0xf bound_ctrl:1
	s_nop 1
	v_add_f32_dpp v8, v8, v8 row_half_mirror row_mask:0xf bank_mask:0xf bound_ctrl:1
	s_nop 1
	v_add_f32_dpp v8, v8, v8 row_mirror row_mask:0xf bank_mask:0xf bound_ctrl:1
	s_nop 0
	v_readlane_b32 s2, v8, 16
	v_readlane_b32 s21, v8, 48
	v_readlane_b32 s0, v8, 0
	v_readlane_b32 s1, v8, 32
	v_mov_b32_e32 v8, s2
	v_mov_b32_e32 v9, s21
	v_pk_add_f32 v[8:9], s[0:1], v[8:9]
	s_nop 0
	v_add_f32_e32 v8, v8, v9
	v_fmamk_f32 v8, v8, 0x3a000000, v35
	v_mul_f32_e32 v9, 0x4b800000, v8
	v_cmp_gt_f32_e32 vcc, s33, v8
	s_nop 1
	v_cndmask_b32_e32 v8, v8, v9, vcc
	v_rsq_f32_e32 v10, v8
	v_lshl_add_u64 v[8:9], v[18:19], 2, s[82:83]
	v_mul_f32_e32 v11, 0x45800000, v10
	v_cndmask_b32_e32 v10, v10, v11, vcc
	v_pk_mul_f32 v[12:13], v[122:123], v[10:11] op_sel_hi:[1,0]
	v_pk_mul_f32 v[14:15], v[120:121], v[10:11] op_sel_hi:[1,0]
	v_cmp_lt_i32_e32 vcc, s5, v36
	v_mov_b32_e32 v2, v174
	v_mov_b32_e32 v3, v175
	v_mov_b32_e32 v4, v176
	v_mov_b32_e32 v5, v177
	v_mov_b32_e32 v116, v178
	v_mov_b32_e32 v117, v179
	v_mov_b32_e32 v118, v180
	v_mov_b32_e32 v119, v181
	v_pk_fma_f32 v[4:5], v[4:5], v[14:15], v[118:119]
	v_pk_fma_f32 v[2:3], v[2:3], v[12:13], v[116:117]
	v_lshl_add_u64 v[14:15], v[90:91], 0, v[92:93]
	v_cvt_pk_bf16_f32 v12, v2, v3
	v_cvt_pk_bf16_f32 v13, v4, v5
	global_store_dwordx2 v[14:15], v[12:13], off nt
	s_and_saveexec_b64 s[0:1], vcc
	s_cbranch_execz .LBB0_2257
	v_lshl_add_u64 v[12:13], v[8:9], 0, v[40:41]
	global_store_dwordx4 v[12:13], v[2:5], off
.LBB0_2257:
	s_or_b64 exec, exec, s[0:1]
	v_lshl_add_u64 v[16:17], v[88:89], 0, s[22:23]
	v_lshl_add_u64 v[12:13], v[88:89], 0, s[24:25]
	v_lshl_add_u64 v[26:27], v[16:17], 0, v[40:41]
	v_lshl_add_u64 v[32:33], v[12:13], 0, v[40:41]
	v_lshl_add_u64 v[18:19], v[18:19], 1, v[42:43]
	v_mov_b32_e32 v106, v111
	v_mov_b32_e32 v11, v10
	v_mov_b32_e32 v104, v109
	v_pk_mul_f32 v[32:33], v[106:107], v[10:11]
	s_waitcnt vmcnt(5)
	v_mov_b32_e32 v26, v238
	v_mov_b32_e32 v27, v239
	v_mov_b32_e32 v28, v240
	v_mov_b32_e32 v29, v241
	v_mov_b32_e32 v88, v242
	v_mov_b32_e32 v89, v243
	v_mov_b32_e32 v90, v244
	v_mov_b32_e32 v91, v245
	global_load_dwordx4 v[238:241], v40, s[98:99] offset:-1024
	global_load_dwordx4 v[242:245], v40, s[100:101] offset:-1024
	v_pk_add_f32 v[26:27], v[26:27], 1.0 op_sel_hi:[1,0]
	v_pk_add_f32 v[28:29], v[28:29], 1.0 op_sel_hi:[1,0]
	v_pk_fma_f32 v[2:3], v[2:3], v[26:27], v[88:89]
	v_pk_fma_f32 v[4:5], v[4:5], v[28:29], v[90:91]
	v_cvt_pk_bf16_f32 v2, v2, v3
	v_mov_b32_e32 v26, v10
	v_cvt_pk_bf16_f32 v3, v4, v5
	global_store_dwordx2 v[18:19], v[2:3], off
	s_nop 0
	v_mov_b32_e32 v27, v10
	v_pk_mul_f32 v[28:29], v[104:105], v[26:27]
	v_mov_b32_e32 v2, v182
	v_mov_b32_e32 v3, v183
	v_mov_b32_e32 v4, v184
	v_mov_b32_e32 v5, v185
	v_mov_b32_e32 v88, v186
	v_mov_b32_e32 v89, v187
	v_mov_b32_e32 v90, v188
	v_mov_b32_e32 v91, v189
	v_pk_fma_f32 v[2:3], v[32:33], v[2:3], v[88:89]
	v_pk_fma_f32 v[4:5], v[28:29], v[4:5], v[90:91]
	v_cvt_pk_bf16_f32 v28, v2, v3
	s_nop 0
	v_cvt_pk_bf16_f32 v29, v4, v5
	global_store_dwordx2 v[14:15], v[28:29], off offset:512 nt
	s_and_saveexec_b64 s[0:1], vcc
	s_cbranch_execz .LBB0_2259
	v_lshl_add_u64 v[28:29], v[8:9], 0, v[40:41]
	global_store_dwordx4 v[28:29], v[2:5], off offset:1024
.LBB0_2259:
	s_or_b64 exec, exec, s[0:1]
	v_mov_b32_e32 v75, v41
	v_lshl_add_u64 v[28:29], v[16:17], 0, v[74:75]
	v_lshl_add_u64 v[28:29], v[12:13], 0, v[74:75]
	v_pk_mul_f32 v[26:27], v[98:99], v[26:27]
	s_waitcnt vmcnt(7)
	v_mov_b32_e32 v88, v246
	v_mov_b32_e32 v89, v247
	v_mov_b32_e32 v90, v248
	v_mov_b32_e32 v91, v249
	v_mov_b32_e32 v104, v250
	v_mov_b32_e32 v105, v251
	v_mov_b32_e32 v106, v252
	v_mov_b32_e32 v107, v253
	global_load_dwordx4 v[246:249], v40, s[98:99]
	global_load_dwordx4 v[250:253], v40, s[100:101]
	v_pk_add_f32 v[32:33], v[88:89], 1.0 op_sel_hi:[1,0]
	v_pk_add_f32 v[28:29], v[90:91], 1.0 op_sel_hi:[1,0]
	v_pk_fma_f32 v[2:3], v[2:3], v[32:33], v[104:105]
	v_pk_fma_f32 v[4:5], v[4:5], v[28:29], v[106:107]
	v_cvt_pk_bf16_f32 v2, v2, v3
	v_pk_mul_f32 v[28:29], v[102:103], v[10:11]
	v_cvt_pk_bf16_f32 v3, v4, v5
	global_store_dwordx2 v[18:19], v[2:3], off offset:512
	s_nop 0
	v_mov_b32_e32 v2, v190
	v_mov_b32_e32 v3, v191
	v_mov_b32_e32 v4, v192
	v_mov_b32_e32 v5, v193
	v_mov_b32_e32 v88, v194
	v_mov_b32_e32 v89, v195
	v_mov_b32_e32 v90, v196
	v_mov_b32_e32 v91, v197
	v_pk_fma_f32 v[4:5], v[26:27], v[4:5], v[90:91]
	v_pk_fma_f32 v[2:3], v[28:29], v[2:3], v[88:89]
	s_nop 0
	v_cvt_pk_bf16_f32 v26, v2, v3
	v_cvt_pk_bf16_f32 v27, v4, v5
	global_store_dwordx2 v[14:15], v[26:27], off offset:1024 nt
	s_and_saveexec_b64 s[0:1], vcc
	s_cbranch_execz .LBB0_2261
	v_lshl_add_u64 v[26:27], v[8:9], 0, v[40:41]
	global_store_dwordx4 v[26:27], v[2:5], off offset:2048
.LBB0_2261:
	s_or_b64 exec, exec, s[0:1]
	v_mov_b32_e32 v77, v41
	v_lshl_add_u64 v[26:27], v[16:17], 0, v[76:77]
	v_lshl_add_u64 v[32:33], v[12:13], 0, v[76:77]
	s_waitcnt vmcnt(9)
	v_mov_b32_e32 v26, v158
	v_mov_b32_e32 v27, v159
	v_mov_b32_e32 v28, v160
	v_mov_b32_e32 v29, v161
	v_mov_b32_e32 v88, v162
	v_mov_b32_e32 v89, v163
	v_mov_b32_e32 v90, v164
	v_mov_b32_e32 v91, v165
	global_load_dwordx4 v[158:161], v40, s[98:99] offset:1024
	global_load_dwordx4 v[162:165], v40, s[100:101] offset:1024
	v_pk_add_f32 v[26:27], v[26:27], 1.0 op_sel_hi:[1,0]
	v_pk_add_f32 v[28:29], v[28:29], 1.0 op_sel_hi:[1,0]
	v_pk_fma_f32 v[2:3], v[2:3], v[26:27], v[88:89]
	v_pk_fma_f32 v[4:5], v[4:5], v[28:29], v[90:91]
	v_cvt_pk_bf16_f32 v2, v2, v3
	v_mov_b32_e32 v26, v10
	v_cvt_pk_bf16_f32 v3, v4, v5
	global_store_dwordx2 v[18:19], v[2:3], off offset:1024
	s_nop 0
	v_mov_b32_e32 v27, v10
	v_pk_mul_f32 v[28:29], v[114:115], v[10:11]
	v_pk_mul_f32 v[32:33], v[112:113], v[26:27]
	v_mov_b32_e32 v2, v198
	v_mov_b32_e32 v3, v199
	v_mov_b32_e32 v4, v200
	v_mov_b32_e32 v5, v201
	v_mov_b32_e32 v88, v202
	v_mov_b32_e32 v89, v203
	v_mov_b32_e32 v90, v204
	v_mov_b32_e32 v91, v205
	v_pk_fma_f32 v[2:3], v[28:29], v[2:3], v[88:89]
	v_pk_fma_f32 v[4:5], v[32:33], v[4:5], v[90:91]
	v_cvt_pk_bf16_f32 v28, v2, v3
	s_nop 0
	v_cvt_pk_bf16_f32 v29, v4, v5
	global_store_dwordx2 v[14:15], v[28:29], off offset:1536 nt
	s_and_saveexec_b64 s[0:1], vcc
	s_cbranch_execz .LBB0_2263
	v_lshl_add_u64 v[28:29], v[8:9], 0, v[40:41]
	global_store_dwordx4 v[28:29], v[2:5], off offset:3072
.LBB0_2263:
	s_or_b64 exec, exec, s[0:1]
	v_mov_b32_e32 v87, v41
	v_lshl_add_u64 v[28:29], v[16:17], 0, v[86:87]
	v_lshl_add_u64 v[28:29], v[12:13], 0, v[86:87]
	v_pk_mul_f32 v[26:27], v[96:97], v[26:27]
	s_waitcnt vmcnt(10)
	v_mov_b32_e32 v88, v238
	v_mov_b32_e32 v89, v239
	v_mov_b32_e32 v90, v240
	v_mov_b32_e32 v91, v241
	v_mov_b32_e32 v102, v242
	v_mov_b32_e32 v103, v243
	v_mov_b32_e32 v104, v244
	v_mov_b32_e32 v105, v245
	global_load_dwordx4 v[238:241], v40, s[98:99] offset:2048
	global_load_dwordx4 v[242:245], v40, s[100:101] offset:2048
	v_pk_add_f32 v[32:33], v[88:89], 1.0 op_sel_hi:[1,0]
	v_pk_add_f32 v[28:29], v[90:91], 1.0 op_sel_hi:[1,0]
	v_pk_fma_f32 v[2:3], v[2:3], v[32:33], v[102:103]
	v_pk_fma_f32 v[4:5], v[4:5], v[28:29], v[104:105]
	v_cvt_pk_bf16_f32 v2, v2, v3
	v_pk_mul_f32 v[28:29], v[100:101], v[10:11]
	v_cvt_pk_bf16_f32 v3, v4, v5
	global_store_dwordx2 v[18:19], v[2:3], off offset:1536
	s_nop 0
	v_mov_b32_e32 v2, v206
	v_mov_b32_e32 v3, v207
	v_mov_b32_e32 v4, v208
	v_mov_b32_e32 v5, v209
	v_mov_b32_e32 v86, v210
	v_mov_b32_e32 v87, v211
	v_mov_b32_e32 v88, v212
	v_mov_b32_e32 v89, v213
	v_pk_fma_f32 v[4:5], v[26:27], v[4:5], v[88:89]
	v_pk_fma_f32 v[2:3], v[28:29], v[2:3], v[86:87]
	s_nop 0
	v_cvt_pk_bf16_f32 v26, v2, v3
	v_cvt_pk_bf16_f32 v27, v4, v5
	global_store_dwordx2 v[14:15], v[26:27], off offset:2048 nt
	s_and_saveexec_b64 s[0:1], vcc
	s_cbranch_execz .LBB0_2265
	v_mov_b32_e32 v85, v41
	v_lshl_add_u64 v[26:27], v[8:9], 0, v[84:85]
	global_store_dwordx4 v[26:27], v[2:5], off
.LBB0_2265:
	s_or_b64 exec, exec, s[0:1]
	v_mov_b32_e32 v85, v41
	v_lshl_add_u64 v[26:27], v[16:17], 0, v[84:85]
	v_lshl_add_u64 v[32:33], v[12:13], 0, v[84:85]
	s_waitcnt vmcnt(10)
	v_mov_b32_e32 v26, v246
	v_mov_b32_e32 v27, v247
	v_mov_b32_e32 v28, v248
	v_mov_b32_e32 v29, v249
	v_mov_b32_e32 v84, v250
	v_mov_b32_e32 v85, v251
	v_mov_b32_e32 v86, v252
	v_mov_b32_e32 v87, v253
	global_load_dwordx4 v[246:249], v40, s[98:99] offset:3072
	global_load_dwordx4 v[250:253], v40, s[100:101] offset:3072
	v_pk_add_f32 v[26:27], v[26:27], 1.0 op_sel_hi:[1,0]
	v_pk_add_f32 v[28:29], v[28:29], 1.0 op_sel_hi:[1,0]
	v_pk_fma_f32 v[2:3], v[2:3], v[26:27], v[84:85]
	v_pk_fma_f32 v[4:5], v[4:5], v[28:29], v[86:87]
	v_cvt_pk_bf16_f32 v2, v2, v3
	v_mov_b32_e32 v26, v10
	v_cvt_pk_bf16_f32 v3, v4, v5
	global_store_dwordx2 v[18:19], v[2:3], off offset:2048
	s_nop 0
	v_mov_b32_e32 v27, v10
	v_pk_mul_f32 v[28:29], v[94:95], v[10:11]
	v_pk_mul_f32 v[24:25], v[24:25], v[26:27]
	v_mov_b32_e32 v2, v214
	v_mov_b32_e32 v3, v215
	v_mov_b32_e32 v4, v216
	v_mov_b32_e32 v5, v217
	v_mov_b32_e32 v84, v218
	v_mov_b32_e32 v85, v219
	v_mov_b32_e32 v86, v220
	v_mov_b32_e32 v87, v221
	v_pk_fma_f32 v[2:3], v[28:29], v[2:3], v[84:85]
	v_pk_fma_f32 v[4:5], v[24:25], v[4:5], v[86:87]
	v_cvt_pk_bf16_f32 v24, v2, v3
	s_nop 0
	v_cvt_pk_bf16_f32 v25, v4, v5
	global_store_dwordx2 v[14:15], v[24:25], off offset:2560 nt
	s_and_saveexec_b64 s[0:1], vcc
	s_cbranch_execz .LBB0_2267
	v_mov_b32_e32 v83, v41
	v_lshl_add_u64 v[24:25], v[8:9], 0, v[82:83]
	global_store_dwordx4 v[24:25], v[2:5], off
.LBB0_2267:
	s_or_b64 exec, exec, s[0:1]
	v_mov_b32_e32 v83, v41
	v_lshl_add_u64 v[24:25], v[16:17], 0, v[82:83]
	v_lshl_add_u64 v[24:25], v[12:13], 0, v[82:83]
	v_pk_mul_f32 v[20:21], v[20:21], v[26:27]
	v_pk_mul_f32 v[22:23], v[22:23], v[10:11]
	s_waitcnt vmcnt(10)
	v_mov_b32_e32 v84, v158
	v_mov_b32_e32 v85, v159
	v_mov_b32_e32 v86, v160
	v_mov_b32_e32 v87, v161
	v_mov_b32_e32 v88, v162
	v_mov_b32_e32 v89, v163
	v_mov_b32_e32 v90, v164
	v_mov_b32_e32 v91, v165
	v_pk_add_f32 v[28:29], v[84:85], 1.0 op_sel_hi:[1,0]
	v_pk_add_f32 v[24:25], v[86:87], 1.0 op_sel_hi:[1,0]
	v_pk_fma_f32 v[2:3], v[2:3], v[28:29], v[88:89]
	v_pk_fma_f32 v[4:5], v[4:5], v[24:25], v[90:91]
	v_cvt_pk_bf16_f32 v2, v2, v3
	s_nop 0
	v_cvt_pk_bf16_f32 v3, v4, v5
	global_store_dwordx2 v[18:19], v[2:3], off offset:2560
	s_nop 0
	v_mov_b32_e32 v2, v222
	v_mov_b32_e32 v3, v223
	v_mov_b32_e32 v4, v224
	v_mov_b32_e32 v5, v225
	v_mov_b32_e32 v82, v226
	v_mov_b32_e32 v83, v227
	v_mov_b32_e32 v84, v228
	v_mov_b32_e32 v85, v229
	v_pk_fma_f32 v[4:5], v[20:21], v[4:5], v[84:85]
	v_pk_fma_f32 v[2:3], v[22:23], v[2:3], v[82:83]
	s_nop 0
	v_cvt_pk_bf16_f32 v20, v2, v3
	v_cvt_pk_bf16_f32 v21, v4, v5
	global_store_dwordx2 v[14:15], v[20:21], off offset:3072 nt
	s_and_saveexec_b64 s[0:1], vcc
	s_cbranch_execz .LBB0_2269
	v_mov_b32_e32 v81, v41
	v_lshl_add_u64 v[20:21], v[8:9], 0, v[80:81]
	global_store_dwordx4 v[20:21], v[2:5], off
.LBB0_2269:
	s_or_b64 exec, exec, s[0:1]
	v_mov_b32_e32 v81, v41
	v_lshl_add_u64 v[20:21], v[16:17], 0, v[80:81]
	v_lshl_add_u64 v[24:25], v[12:13], 0, v[80:81]
	s_waitcnt vmcnt(8)
	v_mov_b32_e32 v20, v238
	v_mov_b32_e32 v21, v239
	v_mov_b32_e32 v22, v240
	v_mov_b32_e32 v23, v241
	v_mov_b32_e32 v24, v242
	v_mov_b32_e32 v25, v243
	v_mov_b32_e32 v26, v244
	v_mov_b32_e32 v27, v245
	v_pk_add_f32 v[20:21], v[20:21], 1.0 op_sel_hi:[1,0]
	v_pk_add_f32 v[22:23], v[22:23], 1.0 op_sel_hi:[1,0]
	v_pk_fma_f32 v[2:3], v[2:3], v[20:21], v[24:25]
	v_pk_fma_f32 v[4:5], v[4:5], v[22:23], v[26:27]
	v_cvt_pk_bf16_f32 v2, v2, v3
	v_mov_b32_e32 v24, v10
	v_cvt_pk_bf16_f32 v3, v4, v5
	global_store_dwordx2 v[18:19], v[2:3], off offset:3072
	s_nop 0
	v_mov_b32_e32 v25, v10
	v_pk_mul_f32 v[10:11], v[30:31], v[10:11]
	v_pk_mul_f32 v[6:7], v[6:7], v[24:25]
	v_mov_b32_e32 v2, v230
	v_mov_b32_e32 v3, v231
	v_mov_b32_e32 v4, v232
	v_mov_b32_e32 v5, v233
	v_mov_b32_e32 v20, v234
	v_mov_b32_e32 v21, v235
	v_mov_b32_e32 v22, v236
	v_mov_b32_e32 v23, v237
	v_pk_fma_f32 v[2:3], v[10:11], v[2:3], v[20:21]
	v_pk_fma_f32 v[4:5], v[6:7], v[4:5], v[22:23]
	v_cvt_pk_bf16_f32 v6, v2, v3
	s_nop 0
	v_cvt_pk_bf16_f32 v7, v4, v5
	global_store_dwordx2 v[14:15], v[6:7], off offset:3584 nt
	s_and_saveexec_b64 s[0:1], vcc
	s_cbranch_execz .LBB0_2271
	v_mov_b32_e32 v79, v41
	v_lshl_add_u64 v[6:7], v[8:9], 0, v[78:79]
	global_store_dwordx4 v[6:7], v[2:5], off
.LBB0_2271:
	s_or_b64 exec, exec, s[0:1]
	v_mov_b32_e32 v79, v41
	v_lshl_add_u64 v[6:7], v[16:17], 0, v[78:79]
	v_lshl_add_u64 v[10:11], v[12:13], 0, v[78:79]
	s_waitcnt vmcnt(6)
	v_mov_b32_e32 v6, v246
	v_mov_b32_e32 v7, v247
	v_mov_b32_e32 v8, v248
	v_mov_b32_e32 v9, v249
	v_mov_b32_e32 v10, v250
	v_mov_b32_e32 v11, v251
	v_mov_b32_e32 v12, v252
	v_mov_b32_e32 v13, v253
	v_pk_add_f32 v[6:7], v[6:7], 1.0 op_sel_hi:[1,0]
	v_pk_add_f32 v[8:9], v[8:9], 1.0 op_sel_hi:[1,0]
	v_pk_fma_f32 v[2:3], v[2:3], v[6:7], v[10:11]
	v_pk_fma_f32 v[4:5], v[4:5], v[8:9], v[12:13]
	v_cvt_pk_bf16_f32 v2, v2, v3
	s_nop 0
	v_cvt_pk_bf16_f32 v3, v4, v5
	global_store_dwordx2 v[18:19], v[2:3], off offset:3584
